# diff+dilated attention: softmax reference starts at 0 and exp2 is taken without the reference subtraction while no row raised it (wave-uniform flag); plus previous trims
# speedup vs baseline: 1.0156x; 1.0057x over previous
; #define LAS __attribute__((address_space(3)))
; #define AT_GLOADK(kt) do { const size_t r_ = rowbase + (size_t)(kt) * 64; \
;         kreg = *(const u32x4*)(Kp + (r_ + lane) * kpitch + wave * 8); \
;         if (MODE == 0 && wave < 4) kreg2 = *(const u32x4*)(proj + (r_ + lane) * NPROJ + 1920 + wave * 8); } while (0)
; #define AT_GLOADV(kt) do { const size_t r_ = rowbase + (size_t)(kt) * 64; \
;         vreg = *(const u32x4*)(Vp + (r_ + 16 * (wave & 3) + (lane >> 2)) * vpitch + (wave >> 2) * 32 + (lane & 3) * 8); } while (0)
; #define AT_LSTOREV(buf) do { LAS unsigned char* d_ = lds + (buf) * AT_BUF; \
;         *(LAS u32x4*)(d_ + AT_V + wave * 1024 + lane * 16) = vreg; } while (0)
; template <int MODE, int NQ>
; __device__ __forceinline__ void attn_unit(LAS unsigned char* lds, const Params& P, int layer, int b, int h, int qb) {
;     ...
;     const int qpos0 = q0 + wave * (32 * NQ) + r32;
;     const int tb0_ = 4 * hi - qpos0 + 2047, ts_ = tb0_ & 3;
;     const LAS unsigned char* tlane = tabb + ts_ * AT_TABC + (tb0_ - ts_) * 4;
;     bf16x8 qf[NC][ND0];
; #pragma unroll
;     for (int jq = 0; jq < NQ; ++jq) {
;         const bf16_t* qrow = Qp + (rowbase + qpos0 + 32 * jq) * qpitch + hi * 8;
; #pragma unroll
;         for (int mp = 0; mp < NMAP; ++mp)
; #pragma unroll
;             for (int d0 = 0; d0 < ND0; ++d0) qf[jq * NMAP + mp][d0] = *(const bf16x8*)(qrow + mp * 32 + d0 * 16);
;     }
;     u32x4 kreg, kreg2 = (u32x4){0u, 0u, 0u, 0u}, vreg;
;     ...
;     float mrun[NC], lrun[NC]; f32x16 o[NC][2];
; #pragma unroll
;     for (int cc = 0; cc < NC; ++cc) { mrun[cc] = -1e20f; lrun[cc] = 0.f; o[cc][0] = f32x16{}; o[cc][1] = f32x16{}; }
;     constexpr int NK = NMAP * ND0;
;     const bf16x8 ones8 = (bf16x8){0x3F80, 0x3F80, 0x3F80, 0x3F80, 0x3F80, 0x3F80, 0x3F80, 0x3F80};
;     const bf16x8 zero8 = (bf16x8){0, 0, 0, 0, 0, 0, 0, 0};
;     bf16x8 kf[NK]; s16x4 vlo[4], vhi[4];
;     ...
;     const int vlane = ((lane >> 4) & 1) * 32 + (lane & 3) * 8 + (4 * hi + ((lane & 15) >> 2)) * 64;
;     const int NT = kt1 - kt0, ks = (MODE != 0) ? (q0 / 64 - kt0) : 0;
;     ...
;     AT_GLOADK(AT_TILE(0)); AT_GLOADV(AT_TILE(0)); AT_LSTOREK(0); AT_LSTOREV(0);
;     if (1 < NT) { AT_GLOADK(AT_TILE(1)); AT_GLOADV(AT_TILE(1)); AT_LSTOREK(1); AT_LSTOREV(1); }
;     __syncthreads();
;     AT_KLOAD(lds, 0);
;     if (wave >= 4) __builtin_amdgcn_s_setprio(1);
;     int bcur = 0;
.LBB0_408:
	v_lshlrev_b32_e32 v185, 2, v6
	v_sub_u32_e32 v4, v185, v4
	v_lshlrev_b32_e32 v186, 3, v6
	v_lshlrev_b32_e32 v6, 1, v2
	v_lshrrev_b32_e32 v2, 2, v2
	s_lshl_b32 s4, s4, 6
	v_add_u32_e32 v4, 0x7ff, v4
	v_and_or_b32 v2, v2, 3, v185
	s_lshl_b32 s7, s6, 2
	v_and_b32_e32 v7, 3, v4
	v_lshlrev_b32_e32 v4, 2, v4
	v_lshlrev_b32_e32 v192, 6, v2
	v_mov_b32_e32 v2, s8
	s_add_u32 s8, s14, s22
	v_mul_u32_u24_e32 v7, 0x4040, v7
	v_and_b32_e32 v4, -16, v4
	s_addc_u32 s9, s15, s23
	v_mov_b32_e32 v14, v1
	v_mov_b32_e32 v15, v1
	v_add3_u32 v191, 0, v7, v4
	v_and_b32_e32 v193, 32, v6
	v_or3_b32 v178, s0, v2, v5
	v_lshl_add_u64 v[180:181], s[8:9], 0, v[0:1]
	v_or_b32_e32 v182, s0, v3
	s_add_u32 s0, s10, s16
	v_mov_b32_e32 v0, v1
	v_mov_b32_e32 v2, v1
	v_mov_b32_e32 v3, v1
	v_mov_b32_e32 v4, v1
	v_mov_b32_e32 v5, v1
	v_mov_b32_e32 v6, v1
	v_mov_b32_e32 v7, v1
	v_mov_b32_e32 v8, v1
	v_mov_b32_e32 v9, v1
	v_mov_b32_e32 v10, v1
	v_mov_b32_e32 v11, v1
	v_mov_b32_e32 v12, v1
	v_mov_b32_e32 v13, v1
	v_mov_b64_e32 v[46:47], v[14:15]
	v_mov_b64_e32 v[62:63], v[14:15]
	v_mov_b64_e32 v[30:31], v[14:15]
	v_mov_b64_e32 v[78:79], v[14:15]
	v_or3_b32 v179, s1, 0, 0
	v_mov_b32_e32 v183, s1
	s_addc_u32 s1, s11, s17
	s_lshl_b32 s5, s6, 10
	s_mov_b32 s8, 0
	v_mov_b32_e32 v187, 0
	v_mov_b32_e32 v197, 0
	v_mov_b32_e32 v198, 0
	v_mov_b32_e32 v188, 0
	v_mov_b64_e32 v[44:45], v[12:13]
	v_mov_b64_e32 v[42:43], v[10:11]
	v_mov_b64_e32 v[40:41], v[8:9]
	v_mov_b64_e32 v[38:39], v[6:7]
	v_mov_b64_e32 v[36:37], v[4:5]
	v_mov_b64_e32 v[34:35], v[2:3]
	v_mov_b64_e32 v[32:33], v[0:1]
	v_mov_b64_e32 v[60:61], v[12:13]
	v_mov_b64_e32 v[58:59], v[10:11]
	v_mov_b64_e32 v[56:57], v[8:9]
	v_mov_b64_e32 v[54:55], v[6:7]
	v_mov_b64_e32 v[52:53], v[4:5]
	v_mov_b64_e32 v[50:51], v[2:3]
	v_mov_b64_e32 v[48:49], v[0:1]
	v_mov_b64_e32 v[28:29], v[12:13]
	v_mov_b64_e32 v[26:27], v[10:11]
	v_mov_b64_e32 v[24:25], v[8:9]
	v_mov_b64_e32 v[22:23], v[6:7]
	v_mov_b64_e32 v[20:21], v[4:5]
	v_mov_b64_e32 v[18:19], v[2:3]
	v_mov_b64_e32 v[16:17], v[0:1]
	v_mov_b64_e32 v[76:77], v[12:13]
	v_mov_b64_e32 v[74:75], v[10:11]
	v_mov_b64_e32 v[72:73], v[8:9]
	v_mov_b64_e32 v[70:71], v[6:7]
	v_mov_b64_e32 v[68:69], v[4:5]
	v_mov_b64_e32 v[66:67], v[2:3]
	v_mov_b64_e32 v[64:65], v[0:1]
	s_mov_b32 s9, 0
	v_mov_b32_e32 v220, s60
	v_mov_b32_e32 v221, s60
	v_mov_b32_e32 v222, s60
	v_mov_b32_e32 v223, s60
	s_mov_b32 s61, 1
	s_branch .LBB0_410

; #define LAS __attribute__((address_space(3)))
; template <int MODE, int NQ>
; __device__ __forceinline__ void attn_unit(LAS unsigned char* lds, const Params& P, int layer, int b, int h, int qb) {
;     ...
;     for (int it = 0; it < NT; ++it) {
;         const int kt = AT_TILE(it);
;         const int bnx = (bcur == 2) ? 0 : bcur + 1, bn2 = (bnx == 2) ? 0 : bnx + 1;
;         const LAS unsigned char* cur = lds + bcur * AT_BUF;
;         const LAS unsigned char* nxt = lds + bnx * AT_BUF;
; #pragma unroll
;         for (int hf = 0; hf < 2; ++hf) {
;             if (it + 2 < NT) { if (hf == 0) AT_GLOADK(AT_TILE(it + 2)); else AT_GLOADV(AT_TILE(it + 2)); }
;             f32x16 sc[NC];
; #pragma unroll
;             for (int cc = 0; cc < NC; ++cc) {
;                 sc[cc] = f32x16{};
; #pragma unroll
;                 for (int d0 = 0; d0 < ND0; ++d0) sc[cc] = __builtin_amdgcn_mfma_f32_32x32x16_bf16(kf[(cc % NMAP) * ND0 + d0], qf[cc][d0], sc[cc], 0, 0, 0);
;             }
;             __builtin_amdgcn_sched_barrier(0);
;             AT_VLOAD(cur, hf);
;             if (hf == 0) AT_KLOAD(cur, 1); else if (it + 1 < NT) AT_KLOAD(nxt, 0);
;             __builtin_amdgcn_sched_barrier(0);
;             bf16x8 pw[NC][2]; float rmrel[NC]; bool alive = false;
; #pragma unroll
;             for (int cc = 0; cc < NC; ++cc) {
;                 f32x16& s0 = sc[cc];
;                 float mn;
;                 if (MODE != 0) {
;                     const LAS f32x4* tp4 = (const LAS f32x4*)(tlane + (kt * 64 + hf * 32) * 4);
;                     float rm = -3e38f;
; #pragma unroll
;                     for (int g = 0; g < 4; ++g) { const f32x4 t4 = tp4[2 * g];
; #pragma unroll
;                         for (int i = 0; i < 4; ++i) { s0[4 * g + i] = s0[4 * g + i] * c + t4[i]; rm = fmaxf(rm, s0[4 * g + i]); } }
;                     rm = xmax(rm);
;                     mn = fmaxf(mrun[cc], rm);
;                     rmrel[cc] = rm;
;                 } else {
;                     float rm = -3e38f;
; #pragma unroll
;                     for (int r = 0; r < 16; ++r) rm = fmaxf(rm, s0[r]);
;                     rm = xmax(rm);
;                     mn = fmaxf(mrun[cc], rm * c);
;                 }
;                 if (__any(mn > mrun[cc] + AT_THR)) {
;                     const float al = fast_exp2(mrun[cc] - mn); lrun[cc] *= al;
; #pragma unroll
.LBB0_410:
	s_mul_i32 s10, s9, 0x5000
	s_add_i32 s16, s10, 0
	s_add_i32 s10, s5, s8
	s_add_i32 s11, s10, 0xffffe000
	s_cmp_gt_u32 s7, 31
	v_add3_u32 v0, s16, v193, v192
	s_cselect_b32 s10, s11, s10
	v_add_u32_e32 v199, v0, v189
	v_add_u32_e32 v0, s10, v191
	s_add_i32 s10, s7, 2
	s_sub_i32 s11, s7, 30
	s_cmp_gt_u32 s10, 31
	s_cselect_b32 s10, s11, s10
	s_ashr_i32 s11, s10, 31
	s_lshl_b64 s[10:11], s[10:11], 6
	v_lshl_add_u64 v[2:3], v[182:183], 0, s[10:11]
	v_mov_b64_e32 v[4:5], s[0:1]
	v_mad_u64_u32 v[4:5], s[14:15], v2, s27, v[4:5]
	v_mad_i32_i24 v5, v3, s27, v5
	global_load_dwordx4 v[2:5], v[4:5], off
	s_waitcnt lgkmcnt(3)
	v_mfma_f32_32x32x16_bf16 v[96:111], v[140:143], v[124:127], 0
	s_waitcnt lgkmcnt(1)
	v_mfma_f32_32x32x16_bf16 v[80:95], v[132:135], v[120:123], 0
	v_mfma_f32_32x32x16_bf16 v[96:111], v[136:139], v[116:119], v[96:111]
	s_waitcnt lgkmcnt(0)
	v_mfma_f32_32x32x16_bf16 v[80:95], v[128:131], v[112:115], v[80:95]
	ds_read_b64_tr_b16 v[148:149], v199 offset:12288
	ds_read_b64_tr_b16 v[150:151], v199 offset:12800
	ds_read_b64_tr_b16 v[144:145], v199 offset:13312
	ds_read_b64_tr_b16 v[146:147], v199 offset:13824
	ds_read_b64_tr_b16 v[140:141], v199 offset:16384
	ds_read_b64_tr_b16 v[142:143], v199 offset:16896
	ds_read_b64_tr_b16 v[136:137], v199 offset:17408
	ds_read_b64_tr_b16 v[138:139], v199 offset:17920
	v_add3_u32 v6, s16, v195, v196
	ds_read_b128 v[132:135], v6 offset:512
	ds_read_b128 v[128:131], v6 offset:2560
	ds_read_b128 v[10:13], v6 offset:4608
	ds_read_b128 v[6:9], v6 offset:6656
	ds_read_b128 v[156:159], v0 offset:61440
	ds_read_b128 v[152:155], v0 offset:61472
	ds_read_b128 v[164:167], v0 offset:61504
	ds_read_b128 v[172:175], v0 offset:61536
	s_waitcnt lgkmcnt(3)
	v_pk_fma_f32 v[160:161], v[96:97], s[34:35], v[156:157] op_sel_hi:[1,0,1]
	v_pk_fma_f32 v[98:99], v[98:99], s[34:35], v[158:159] op_sel_hi:[1,0,1]
	v_max3_f32 v96, v160, s68, v161
	s_waitcnt lgkmcnt(2)
	v_pk_fma_f32 v[14:15], v[100:101], s[34:35], v[152:153] op_sel_hi:[1,0,1]
	v_max3_f32 v96, v96, v98, v99
	v_max3_f32 v100, v96, v14, v15
	v_pk_fma_f32 v[96:97], v[102:103], s[34:35], v[154:155] op_sel_hi:[1,0,1]
	s_waitcnt lgkmcnt(1)
	v_pk_fma_f32 v[104:105], v[104:105], s[34:35], v[164:165] op_sel_hi:[1,0,1]
	v_max3_f32 v100, v100, v96, v97
	v_max3_f32 v102, v100, v104, v105
	v_pk_fma_f32 v[100:101], v[106:107], s[34:35], v[166:167] op_sel_hi:[1,0,1]
	s_nop 0
	v_max3_f32 v106, v102, v100, v101
	s_waitcnt lgkmcnt(0)
	v_pk_fma_f32 v[102:103], v[108:109], s[34:35], v[172:173] op_sel_hi:[1,0,1]
	s_nop 0
	v_max3_f32 v108, v106, v102, v103
	v_pk_fma_f32 v[106:107], v[110:111], s[34:35], v[174:175] op_sel_hi:[1,0,1]
	s_nop 0
	v_max3_f32 v108, v108, v106, v107
	v_mov_b32_e32 v109, v108
	s_nop 1
	v_permlane32_swap_b32_e32 v108, v109
	v_max_f32_e32 v108, v108, v109
	v_max_f32_e32 v200, v198, v108
	v_add_f32_e32 v109, 0x41000000, v198
	v_cmp_gt_f32_e32 vcc, v200, v109
	s_cbranch_vccz .LBB0_412
	v_sub_f32_e32 v109, v198, v200
	s_mov_b32 s61, 0
	v_exp_f32_e32 v110, v109
	s_nop 0
	v_mul_f32_e32 v188, v188, v110
	v_pk_mul_f32 v[78:79], v[78:79], v[110:111] op_sel_hi:[1,0]
	v_pk_mul_f32 v[76:77], v[76:77], v[110:111] op_sel_hi:[1,0]
	v_pk_mul_f32 v[74:75], v[74:75], v[110:111] op_sel_hi:[1,0]
	v_pk_mul_f32 v[72:73], v[72:73], v[110:111] op_sel_hi:[1,0]
	v_pk_mul_f32 v[70:71], v[70:71], v[110:111] op_sel_hi:[1,0]
	v_pk_mul_f32 v[68:69], v[68:69], v[110:111] op_sel_hi:[1,0]
	v_pk_mul_f32 v[66:67], v[66:67], v[110:111] op_sel_hi:[1,0]
	v_pk_mul_f32 v[64:65], v[64:65], v[110:111] op_sel_hi:[1,0]
	v_pk_mul_f32 v[30:31], v[30:31], v[110:111] op_sel_hi:[1,0]
	v_pk_mul_f32 v[28:29], v[28:29], v[110:111] op_sel_hi:[1,0]
	v_pk_mul_f32 v[26:27], v[26:27], v[110:111] op_sel_hi:[1,0]
	v_pk_mul_f32 v[24:25], v[24:25], v[110:111] op_sel_hi:[1,0]
	v_pk_mul_f32 v[22:23], v[22:23], v[110:111] op_sel_hi:[1,0]
	v_pk_mul_f32 v[20:21], v[20:21], v[110:111] op_sel_hi:[1,0]
	v_pk_mul_f32 v[18:19], v[18:19], v[110:111] op_sel_hi:[1,0]
	v_pk_mul_f32 v[16:17], v[16:17], v[110:111] op_sel_hi:[1,0]
	s_branch .LBB0_413

; __device__ __forceinline__ unsigned cvtpk(float lo, float hi) { f32x2 v = {lo, hi}; bf16x2_t b = __builtin_convertvector(v, bf16x2_t); return __builtin_bit_cast(unsigned, b); }
; __device__ __forceinline__ float fast_exp2(float x) { return __builtin_amdgcn_exp2f(x); }
; template <int MODE, int NQ>
; __device__ __forceinline__ void attn_unit(LAS unsigned char* lds, const Params& P, int layer, int b, int h, int qb) {
;     ...
;                 mn = mrun[cc];
;                 if (MODE != 0) rmrel[cc] -= mn;
;                 const bool dead = (MODE != 0) && __all(rmrel[cc] < -136.f);
;                 if (dead) { pw[cc][0] = zero8; pw[cc][1] = zero8; }
;                 else {
;                     alive = true;
;                     if (MODE != 0) {
; #pragma unroll
;                         for (int r = 0; r < 16; ++r) s0[r] = fast_exp2(s0[r] - mn);
;                     } else {
;                         const float nm = -mn;
; #pragma unroll
;                         for (int r = 0; r < 16; ++r) s0[r] = fast_exp2(__builtin_fmaf(s0[r], c, nm));
;                     }
;                     u32x4 w;
;                     w.x = cvtpk(s0[0], s0[1]); w.y = cvtpk(s0[2], s0[3]); w.z = cvtpk(s0[4], s0[5]); w.w = cvtpk(s0[6], s0[7]); pw[cc][0] = __builtin_bit_cast(bf16x8, w);
;                     w.x = cvtpk(s0[8], s0[9]); w.y = cvtpk(s0[10], s0[11]); w.z = cvtpk(s0[12], s0[13]); w.w = cvtpk(s0[14], s0[15]); pw[cc][1] = __builtin_bit_cast(bf16x8, w);
;                     f32x16 t = __builtin_amdgcn_mfma_f32_32x32x16_bf16(ones8, pw[cc][0], f32x16{}, 0, 0, 0);
;                     t = __builtin_amdgcn_mfma_f32_32x32x16_bf16(ones8, pw[cc][1], t, 0, 0, 0);
;                     lrun[cc] += t[0];
.LBB0_413:
	v_sub_f32_e32 v108, v108, v200
	v_cmp_gt_f32_e32 vcc, s30, v108
	s_cmp_lg_u64 vcc, exec
	s_cselect_b64 s[14:15], -1, 0
	s_cmp_eq_u64 vcc, exec
	s_cbranch_scc1 .LBB0_415
	s_cmp_lg_u32 s61, 0
	s_cbranch_scc1 .Lr0_A1_fast
	v_sub_f32_e32 v108, v160, v200
	v_sub_f32_e32 v109, v161, v200
	v_sub_f32_e32 v98, v98, v200
	v_sub_f32_e32 v99, v99, v200
	v_sub_f32_e32 v14, v14, v200
	v_sub_f32_e32 v15, v15, v200
	v_sub_f32_e32 v96, v96, v200
	v_sub_f32_e32 v97, v97, v200
	v_exp_f32_e32 v108, v108
	v_exp_f32_e32 v109, v109
	v_exp_f32_e32 v98, v98
	v_exp_f32_e32 v99, v99
	v_exp_f32_e32 v14, v14
	v_exp_f32_e32 v15, v15
	v_exp_f32_e32 v96, v96
	v_exp_f32_e32 v97, v97
	v_sub_f32_e32 v104, v104, v200
	v_sub_f32_e32 v105, v105, v200
	v_sub_f32_e32 v100, v100, v200
	v_sub_f32_e32 v101, v101, v200
	v_sub_f32_e32 v102, v102, v200
	v_sub_f32_e32 v103, v103, v200
	v_sub_f32_e32 v106, v106, v200
	v_sub_f32_e32 v107, v107, v200
	v_exp_f32_e32 v104, v104
	v_exp_f32_e32 v105, v105
	v_exp_f32_e32 v100, v100
	v_exp_f32_e32 v101, v101
	v_exp_f32_e32 v102, v102
	v_exp_f32_e32 v103, v103
	v_exp_f32_e32 v106, v106
	v_exp_f32_e32 v107, v107
.Lr0_A1_join:
	v_cvt_pk_bf16_f32 v168, v108, v109
	v_cvt_pk_bf16_f32 v169, v98, v99
	v_cvt_pk_bf16_f32 v170, v14, v15
	v_cvt_pk_bf16_f32 v171, v96, v97
	v_cvt_pk_bf16_f32 v160, v104, v105
	v_cvt_pk_bf16_f32 v161, v100, v101
	v_cvt_pk_bf16_f32 v162, v102, v103
	v_cvt_pk_bf16_f32 v163, v106, v107
	v_mfma_f32_32x32x16_bf16 v[96:111], v[220:223], v[168:171], 0
	s_nop 0
	v_mfma_f32_32x32x16_bf16 v[96:111], v[220:223], v[160:163], v[96:111]
	s_nop 11
	v_add_f32_e32 v188, v188, v96
	s_branch .LBB0_416

; #define LAS __attribute__((address_space(3)))
; __device__ __forceinline__ float fast_exp2(float x) { return __builtin_amdgcn_exp2f(x); }
; template <int MODE, int NQ>
; __device__ __forceinline__ void attn_unit(LAS unsigned char* lds, const Params& P, int layer, int b, int h, int qb) {
;     ...
;             for (int cc = 0; cc < NC; ++cc) {
;                 f32x16& s0 = sc[cc];
;                 float mn;
;                 if (MODE != 0) {
;                     const LAS f32x4* tp4 = (const LAS f32x4*)(tlane + (kt * 64 + hf * 32) * 4);
;                     float rm = -3e38f;
; #pragma unroll
;                     for (int g = 0; g < 4; ++g) { const f32x4 t4 = tp4[2 * g];
; #pragma unroll
;                         for (int i = 0; i < 4; ++i) { s0[4 * g + i] = s0[4 * g + i] * c + t4[i]; rm = fmaxf(rm, s0[4 * g + i]); } }
;                     rm = xmax(rm);
;                     mn = fmaxf(mrun[cc], rm);
;                     rmrel[cc] = rm;
;                 } else {
;                     float rm = -3e38f;
; #pragma unroll
;                     for (int r = 0; r < 16; ++r) rm = fmaxf(rm, s0[r]);
;                     rm = xmax(rm);
;                     mn = fmaxf(mrun[cc], rm * c);
;                 }
;                 if (__any(mn > mrun[cc] + AT_THR)) {
;                     const float al = fast_exp2(mrun[cc] - mn); lrun[cc] *= al;
; #pragma unroll
;                     for (int r = 0; r < 16; ++r) { o[cc][0][r] *= al; o[cc][1][r] *= al; }
;                     mrun[cc] = mn;
;                 }
;                 mn = mrun[cc];
;                 if (MODE != 0) rmrel[cc] -= mn;
;                 const bool dead = (MODE != 0) && __all(rmrel[cc] < -136.f);
;                 if (dead) { pw[cc][0] = zero8; pw[cc][1] = zero8; }
;                 else {
;                     alive = true;
;                     if (MODE != 0) {
; #pragma unroll
;                         for (int r = 0; r < 16; ++r) s0[r] = fast_exp2(s0[r] - mn);
;                     } else {
;                         const float nm = -mn;
; #pragma unroll
;                         for (int r = 0; r < 16; ++r) s0[r] = fast_exp2(__builtin_fmaf(s0[r], c, nm));
;                     }
;                     u32x4 w;
;                     w.x = cvtpk(s0[0], s0[1]); w.y = cvtpk(s0[2], s0[3]); w.z = cvtpk(s0[4], s0[5]); w.w = cvtpk(s0[6], s0[7]); pw[cc][0] = __builtin_bit_cast(bf16x8, w);
.LBB0_416:
	v_fmamk_f32 v99, v80, 0x3e8293ee, v156
	v_fmamk_f32 v96, v81, 0x3e8293ee, v157
	v_max3_f32 v14, v99, s68, v96
	v_fmamk_f32 v97, v82, 0x3e8293ee, v158
	v_fmac_f32_e32 v159, 0x3e8293ee, v83
	v_max3_f32 v14, v14, v97, v159
	v_fmamk_f32 v98, v84, 0x3e8293ee, v152
	v_fmamk_f32 v83, v85, 0x3e8293ee, v153
	v_max3_f32 v14, v14, v98, v83
	v_fmamk_f32 v84, v86, 0x3e8293ee, v154
	v_fmac_f32_e32 v155, 0x3e8293ee, v87
	v_max3_f32 v14, v14, v84, v155
	v_fmamk_f32 v85, v88, 0x3e8293ee, v164
	v_fmamk_f32 v80, v89, 0x3e8293ee, v165
	v_max3_f32 v14, v14, v85, v80
	v_fmamk_f32 v81, v90, 0x3e8293ee, v166
	v_fmac_f32_e32 v167, 0x3e8293ee, v91
	v_max3_f32 v15, v14, v81, v167
	v_fmamk_f32 v82, v92, 0x3e8293ee, v172
	v_fmamk_f32 v14, v93, 0x3e8293ee, v173
	v_max3_f32 v86, v15, v82, v14
	v_fmamk_f32 v15, v94, 0x3e8293ee, v174
	v_fmac_f32_e32 v175, 0x3e8293ee, v95
	v_max3_f32 v86, v86, v15, v175
	v_mov_b32_e32 v87, v86
	s_nop 1
	v_permlane32_swap_b32_e32 v86, v87
	v_max_f32_e32 v86, v86, v87
	v_max_f32_e32 v201, v197, v86
	v_add_f32_e32 v87, 0x41000000, v197
	v_cmp_gt_f32_e32 vcc, v201, v87
	s_cbranch_vccz .LBB0_419
	v_sub_f32_e32 v87, v197, v201
	s_mov_b32 s61, 0
	v_exp_f32_e32 v88, v87
	s_nop 0
	v_mul_f32_e32 v187, v187, v88
	v_pk_mul_f32 v[62:63], v[62:63], v[88:89] op_sel_hi:[1,0]
	v_pk_mul_f32 v[60:61], v[60:61], v[88:89] op_sel_hi:[1,0]
	v_pk_mul_f32 v[58:59], v[58:59], v[88:89] op_sel_hi:[1,0]
	v_pk_mul_f32 v[56:57], v[56:57], v[88:89] op_sel_hi:[1,0]
	v_pk_mul_f32 v[54:55], v[54:55], v[88:89] op_sel_hi:[1,0]
	v_pk_mul_f32 v[52:53], v[52:53], v[88:89] op_sel_hi:[1,0]
	v_pk_mul_f32 v[50:51], v[50:51], v[88:89] op_sel_hi:[1,0]
	v_pk_mul_f32 v[48:49], v[48:49], v[88:89] op_sel_hi:[1,0]
	v_pk_mul_f32 v[46:47], v[46:47], v[88:89] op_sel_hi:[1,0]
	v_pk_mul_f32 v[44:45], v[44:45], v[88:89] op_sel_hi:[1,0]
	v_pk_mul_f32 v[42:43], v[42:43], v[88:89] op_sel_hi:[1,0]
	v_pk_mul_f32 v[40:41], v[40:41], v[88:89] op_sel_hi:[1,0]
	v_pk_mul_f32 v[38:39], v[38:39], v[88:89] op_sel_hi:[1,0]
	v_pk_mul_f32 v[36:37], v[36:37], v[88:89] op_sel_hi:[1,0]
	v_pk_mul_f32 v[34:35], v[34:35], v[88:89] op_sel_hi:[1,0]
	v_pk_mul_f32 v[32:33], v[32:33], v[88:89] op_sel_hi:[1,0]
	v_sub_f32_e32 v86, v86, v201
	v_cmp_gt_f32_e32 vcc, s30, v86
	s_cmp_eq_u64 vcc, exec
	s_cbranch_scc1 .LBB0_420
.LBB0_418:
	s_cmp_lg_u32 s61, 0
	s_cbranch_scc1 .Lr0_A2_fast
	v_sub_f32_e32 v86, v99, v201
	v_sub_f32_e32 v87, v96, v201
	v_sub_f32_e32 v88, v97, v201
	v_sub_f32_e32 v89, v159, v201
	v_sub_f32_e32 v90, v98, v201
	v_sub_f32_e32 v83, v83, v201
	v_sub_f32_e32 v84, v84, v201
	v_sub_f32_e32 v91, v155, v201
	v_exp_f32_e32 v86, v86
	v_exp_f32_e32 v87, v87
	v_exp_f32_e32 v88, v88
	v_exp_f32_e32 v89, v89
	v_exp_f32_e32 v90, v90
	v_exp_f32_e32 v83, v83
	v_exp_f32_e32 v84, v84
	v_exp_f32_e32 v91, v91
	v_sub_f32_e32 v85, v85, v201
	v_sub_f32_e32 v80, v80, v201
	v_sub_f32_e32 v81, v81, v201
	v_sub_f32_e32 v92, v167, v201
	v_sub_f32_e32 v82, v82, v201
	v_sub_f32_e32 v14, v14, v201
	v_sub_f32_e32 v15, v15, v201
	v_sub_f32_e32 v93, v175, v201
	v_exp_f32_e32 v85, v85
	v_exp_f32_e32 v80, v80
	v_exp_f32_e32 v81, v81
	v_exp_f32_e32 v92, v92
	v_exp_f32_e32 v82, v82
	v_exp_f32_e32 v14, v14
	v_exp_f32_e32 v15, v15
	v_exp_f32_e32 v93, v93
.Lr0_A2_join:
	v_cvt_pk_bf16_f32 v100, v86, v87
	v_cvt_pk_bf16_f32 v101, v88, v89
	v_cvt_pk_bf16_f32 v102, v90, v83
	v_cvt_pk_bf16_f32 v103, v84, v91
	v_cvt_pk_bf16_f32 v96, v85, v80
	v_cvt_pk_bf16_f32 v97, v81, v92
	v_cvt_pk_bf16_f32 v98, v82, v14
	v_cvt_pk_bf16_f32 v99, v15, v93
	v_mfma_f32_32x32x16_bf16 v[80:95], v[220:223], v[100:103], 0
	s_nop 0
	v_mfma_f32_32x32x16_bf16 v[80:95], v[220:223], v[96:99], v[80:95]
	s_nop 11
	v_add_f32_e32 v187, v187, v80
	s_cbranch_execnz .LBB0_421
	s_branch .LBB0_422

; template <int MODE, int NQ>
; __device__ __forceinline__ void attn_unit(LAS unsigned char* lds, const Params& P, int layer, int b, int h, int qb) {
;     ...
;         const int bnx = (bcur == 2) ? 0 : bcur + 1, bn2 = (bnx == 2) ? 0 : bnx + 1;
;         const LAS unsigned char* cur = lds + bcur * AT_BUF;
;         const LAS unsigned char* nxt = lds + bnx * AT_BUF;
; #pragma unroll
;         for (int hf = 0; hf < 2; ++hf) {
;             if (it + 2 < NT) { if (hf == 0) AT_GLOADK(AT_TILE(it + 2)); else AT_GLOADV(AT_TILE(it + 2)); }
;             f32x16 sc[NC];
; #pragma unroll
;             for (int cc = 0; cc < NC; ++cc) {
;                 sc[cc] = f32x16{};
; #pragma unroll
;                 for (int d0 = 0; d0 < ND0; ++d0) sc[cc] = __builtin_amdgcn_mfma_f32_32x32x16_bf16(kf[(cc % NMAP) * ND0 + d0], qf[cc][d0], sc[cc], 0, 0, 0);
;             }
;             __builtin_amdgcn_sched_barrier(0);
;             AT_VLOAD(cur, hf);
;             if (hf == 0) AT_KLOAD(cur, 1); else if (it + 1 < NT) AT_KLOAD(nxt, 0);
;             __builtin_amdgcn_sched_barrier(0);
;             bf16x8 pw[NC][2]; float rmrel[NC]; bool alive = false;
; #pragma unroll
;             for (int cc = 0; cc < NC; ++cc) {
;                 f32x16& s0 = sc[cc];
;                 float mn;
;                 if (MODE != 0) {
;                     const LAS f32x4* tp4 = (const LAS f32x4*)(tlane + (kt * 64 + hf * 32) * 4);
;                     float rm = -3e38f;
; #pragma unroll
;                     for (int g = 0; g < 4; ++g) { const f32x4 t4 = tp4[2 * g];
; #pragma unroll
;                         for (int i = 0; i < 4; ++i) { s0[4 * g + i] = s0[4 * g + i] * c + t4[i]; rm = fmaxf(rm, s0[4 * g + i]); } }
;                     rm = xmax(rm);
;                     mn = fmaxf(mrun[cc], rm);
;                     rmrel[cc] = rm;
;                 } else {
;                     float rm = -3e38f;
; #pragma unroll
;                     for (int r = 0; r < 16; ++r) rm = fmaxf(rm, s0[r]);
;                     rm = xmax(rm);
;                     mn = fmaxf(mrun[cc], rm * c);
;                 }
;                 if (__any(mn > mrun[cc] + AT_THR)) {
;                     const float al = fast_exp2(mrun[cc] - mn); lrun[cc] *= al;
; #pragma unroll
;                     for (int r = 0; r < 16; ++r) { o[cc][0][r] *= al; o[cc][1][r] *= al; }
;                     mrun[cc] = mn;
;                 }
.LBB0_422:
	s_add_i32 s14, s9, 1
	s_cmp_lg_u32 s9, 2
	s_cselect_b32 s9, s14, 0
	v_lshl_add_u64 v[14:15], v[178:179], 0, s[10:11]
	s_mul_i32 s15, s9, 0x5000
	v_mad_u64_u32 v[80:81], s[10:11], v14, s27, v[180:181]
	s_add_i32 s10, s15, 0x5000
	s_cmp_lg_u32 s9, 2
	s_cselect_b32 s14, s10, 0
	v_mad_i32_i24 v81, v15, s27, v81
	v_add_u32_e32 v202, s14, v194
	s_waitcnt vmcnt(0)
	ds_write_b128 v202, v[2:5]
	global_load_dwordx4 v[2:5], v[80:81], off
	v_mfma_f32_32x32x16_bf16 v[96:111], v[132:135], v[124:127], 0
	v_mfma_f32_32x32x16_bf16 v[80:95], v[10:13], v[120:123], 0
	v_mfma_f32_32x32x16_bf16 v[96:111], v[128:131], v[116:119], v[96:111]
	v_mfma_f32_32x32x16_bf16 v[80:95], v[6:9], v[112:115], v[80:95]
	ds_read_b64_tr_b16 v[148:149], v199 offset:14336
	ds_read_b64_tr_b16 v[150:151], v199 offset:14848
	ds_read_b64_tr_b16 v[144:145], v199 offset:15360
	ds_read_b64_tr_b16 v[146:147], v199 offset:15872
	ds_read_b64_tr_b16 v[10:11], v199 offset:18432
	ds_read_b64_tr_b16 v[12:13], v199 offset:18944
	ds_read_b64_tr_b16 v[6:7], v199 offset:19456
	ds_read_b64_tr_b16 v[8:9], v199 offset:19968
	v_add_u32_e32 v14, s15, v190
	ds_read_b128 v[140:143], v14
	ds_read_b128 v[136:139], v14 offset:2048
	ds_read_b128 v[132:135], v14 offset:4096
	ds_read_b128 v[128:131], v14 offset:6144
	ds_read_b128 v[156:159], v0 offset:61568
	ds_read_b128 v[152:155], v0 offset:61600
	ds_read_b128 v[164:167], v0 offset:61632
	ds_read_b128 v[172:175], v0 offset:61664
	s_waitcnt lgkmcnt(3)
	v_pk_fma_f32 v[160:161], v[96:97], s[34:35], v[156:157] op_sel_hi:[1,0,1]
	v_pk_fma_f32 v[98:99], v[98:99], s[34:35], v[158:159] op_sel_hi:[1,0,1]
	v_max3_f32 v96, v160, s68, v161
	s_waitcnt lgkmcnt(2)
	v_pk_fma_f32 v[14:15], v[100:101], s[34:35], v[152:153] op_sel_hi:[1,0,1]
	v_max3_f32 v96, v96, v98, v99
	v_max3_f32 v100, v96, v14, v15
	v_pk_fma_f32 v[96:97], v[102:103], s[34:35], v[154:155] op_sel_hi:[1,0,1]
	s_waitcnt lgkmcnt(1)
	v_pk_fma_f32 v[104:105], v[104:105], s[34:35], v[164:165] op_sel_hi:[1,0,1]
	v_max3_f32 v100, v100, v96, v97
	v_max3_f32 v0, v100, v104, v105
	v_pk_fma_f32 v[100:101], v[106:107], s[34:35], v[166:167] op_sel_hi:[1,0,1]
	s_waitcnt lgkmcnt(0)
	v_pk_fma_f32 v[102:103], v[108:109], s[34:35], v[172:173] op_sel_hi:[1,0,1]
	v_max3_f32 v0, v0, v100, v101
	v_max3_f32 v0, v0, v102, v103
	v_pk_fma_f32 v[106:107], v[110:111], s[34:35], v[174:175] op_sel_hi:[1,0,1]
	s_nop 0
	v_max3_f32 v0, v0, v106, v107
	v_mov_b32_e32 v108, v0
	s_nop 1
	v_permlane32_swap_b32_e32 v0, v108
	v_max_f32_e32 v0, v0, v108
	v_max_f32_e32 v198, v200, v0
	v_add_f32_e32 v108, 0x41000000, v200
	v_cmp_gt_f32_e32 vcc, v198, v108
	s_cbranch_vccz .LBB0_424
	v_sub_f32_e32 v108, v200, v198
	s_mov_b32 s61, 0
	v_exp_f32_e32 v108, v108
	s_nop 0
	v_mul_f32_e32 v188, v188, v108
	v_pk_mul_f32 v[78:79], v[78:79], v[108:109] op_sel_hi:[1,0]
	v_pk_mul_f32 v[76:77], v[76:77], v[108:109] op_sel_hi:[1,0]
	v_pk_mul_f32 v[74:75], v[74:75], v[108:109] op_sel_hi:[1,0]
	v_pk_mul_f32 v[72:73], v[72:73], v[108:109] op_sel_hi:[1,0]
	v_pk_mul_f32 v[70:71], v[70:71], v[108:109] op_sel_hi:[1,0]
	v_pk_mul_f32 v[68:69], v[68:69], v[108:109] op_sel_hi:[1,0]
	v_pk_mul_f32 v[66:67], v[66:67], v[108:109] op_sel_hi:[1,0]
	v_pk_mul_f32 v[64:65], v[64:65], v[108:109] op_sel_hi:[1,0]
	v_pk_mul_f32 v[30:31], v[30:31], v[108:109] op_sel_hi:[1,0]
	v_pk_mul_f32 v[28:29], v[28:29], v[108:109] op_sel_hi:[1,0]
	v_pk_mul_f32 v[26:27], v[26:27], v[108:109] op_sel_hi:[1,0]
	v_pk_mul_f32 v[24:25], v[24:25], v[108:109] op_sel_hi:[1,0]
	v_pk_mul_f32 v[22:23], v[22:23], v[108:109] op_sel_hi:[1,0]
	v_pk_mul_f32 v[20:21], v[20:21], v[108:109] op_sel_hi:[1,0]
	v_pk_mul_f32 v[18:19], v[18:19], v[108:109] op_sel_hi:[1,0]
	v_pk_mul_f32 v[16:17], v[16:17], v[108:109] op_sel_hi:[1,0]
	s_branch .LBB0_425

; __device__ __forceinline__ unsigned cvtpk(float lo, float hi) { f32x2 v = {lo, hi}; bf16x2_t b = __builtin_convertvector(v, bf16x2_t); return __builtin_bit_cast(unsigned, b); }
; __device__ __forceinline__ float fast_exp2(float x) { return __builtin_amdgcn_exp2f(x); }
; template <int MODE, int NQ>
; __device__ __forceinline__ void attn_unit(LAS unsigned char* lds, const Params& P, int layer, int b, int h, int qb) {
;     ...
;                 mn = mrun[cc];
;                 if (MODE != 0) rmrel[cc] -= mn;
;                 const bool dead = (MODE != 0) && __all(rmrel[cc] < -136.f);
;                 if (dead) { pw[cc][0] = zero8; pw[cc][1] = zero8; }
;                 else {
;                     alive = true;
;                     if (MODE != 0) {
; #pragma unroll
;                         for (int r = 0; r < 16; ++r) s0[r] = fast_exp2(s0[r] - mn);
;                     } else {
;                         const float nm = -mn;
; #pragma unroll
;                         for (int r = 0; r < 16; ++r) s0[r] = fast_exp2(__builtin_fmaf(s0[r], c, nm));
;                     }
;                     u32x4 w;
;                     w.x = cvtpk(s0[0], s0[1]); w.y = cvtpk(s0[2], s0[3]); w.z = cvtpk(s0[4], s0[5]); w.w = cvtpk(s0[6], s0[7]); pw[cc][0] = __builtin_bit_cast(bf16x8, w);
;                     w.x = cvtpk(s0[8], s0[9]); w.y = cvtpk(s0[10], s0[11]); w.z = cvtpk(s0[12], s0[13]); w.w = cvtpk(s0[14], s0[15]); pw[cc][1] = __builtin_bit_cast(bf16x8, w);
;                     f32x16 t = __builtin_amdgcn_mfma_f32_32x32x16_bf16(ones8, pw[cc][0], f32x16{}, 0, 0, 0);
;                     t = __builtin_amdgcn_mfma_f32_32x32x16_bf16(ones8, pw[cc][1], t, 0, 0, 0);
;                     lrun[cc] += t[0];
.LBB0_425:
	v_sub_f32_e32 v0, v0, v198
	v_cmp_gt_f32_e32 vcc, s30, v0
	s_cmp_lg_u64 vcc, exec
	s_cselect_b64 s[10:11], -1, 0
	s_cmp_eq_u64 vcc, exec
	s_cbranch_scc1 .LBB0_427
	s_cmp_lg_u32 s61, 0
	s_cbranch_scc1 .Lr0_A3_fast
	v_sub_f32_e32 v0, v160, v198
	v_sub_f32_e32 v108, v161, v198
	v_sub_f32_e32 v98, v98, v198
	v_sub_f32_e32 v99, v99, v198
	v_sub_f32_e32 v14, v14, v198
	v_sub_f32_e32 v15, v15, v198
	v_sub_f32_e32 v96, v96, v198
	v_sub_f32_e32 v97, v97, v198
	v_exp_f32_e32 v0, v0
	v_exp_f32_e32 v108, v108
	v_exp_f32_e32 v98, v98
	v_exp_f32_e32 v99, v99
	v_exp_f32_e32 v14, v14
	v_exp_f32_e32 v15, v15
	v_exp_f32_e32 v96, v96
	v_exp_f32_e32 v97, v97
	v_sub_f32_e32 v104, v104, v198
	v_sub_f32_e32 v105, v105, v198
	v_sub_f32_e32 v100, v100, v198
	v_sub_f32_e32 v101, v101, v198
	v_sub_f32_e32 v102, v102, v198
	v_sub_f32_e32 v103, v103, v198
	v_sub_f32_e32 v106, v106, v198
	v_sub_f32_e32 v107, v107, v198
	v_exp_f32_e32 v104, v104
	v_exp_f32_e32 v105, v105
	v_exp_f32_e32 v100, v100
	v_exp_f32_e32 v101, v101
	v_exp_f32_e32 v102, v102
	v_exp_f32_e32 v103, v103
	v_exp_f32_e32 v106, v106
	v_exp_f32_e32 v107, v107
.Lr0_A3_join:
	v_cvt_pk_bf16_f32 v168, v0, v108
	v_cvt_pk_bf16_f32 v169, v98, v99
	v_cvt_pk_bf16_f32 v170, v14, v15
	v_cvt_pk_bf16_f32 v171, v96, v97
	v_cvt_pk_bf16_f32 v160, v104, v105
	v_cvt_pk_bf16_f32 v161, v100, v101
	v_cvt_pk_bf16_f32 v162, v102, v103
	v_cvt_pk_bf16_f32 v163, v106, v107
	v_mfma_f32_32x32x16_bf16 v[96:111], v[220:223], v[168:171], 0
	s_nop 0
	v_mfma_f32_32x32x16_bf16 v[96:111], v[220:223], v[160:163], v[96:111]
	s_nop 11
	v_add_f32_e32 v188, v188, v96
	s_branch .LBB0_428

; #define LAS __attribute__((address_space(3)))
; __device__ __forceinline__ float fast_exp2(float x) { return __builtin_amdgcn_exp2f(x); }
; template <int MODE, int NQ>
; __device__ __forceinline__ void attn_unit(LAS unsigned char* lds, const Params& P, int layer, int b, int h, int qb) {
;     ...
;             for (int cc = 0; cc < NC; ++cc) {
;                 f32x16& s0 = sc[cc];
;                 float mn;
;                 if (MODE != 0) {
;                     const LAS f32x4* tp4 = (const LAS f32x4*)(tlane + (kt * 64 + hf * 32) * 4);
;                     float rm = -3e38f;
; #pragma unroll
;                     for (int g = 0; g < 4; ++g) { const f32x4 t4 = tp4[2 * g];
; #pragma unroll
;                         for (int i = 0; i < 4; ++i) { s0[4 * g + i] = s0[4 * g + i] * c + t4[i]; rm = fmaxf(rm, s0[4 * g + i]); } }
;                     rm = xmax(rm);
;                     mn = fmaxf(mrun[cc], rm);
;                     rmrel[cc] = rm;
;                 } else {
;                     float rm = -3e38f;
; #pragma unroll
;                     for (int r = 0; r < 16; ++r) rm = fmaxf(rm, s0[r]);
;                     rm = xmax(rm);
;                     mn = fmaxf(mrun[cc], rm * c);
;                 }
;                 if (__any(mn > mrun[cc] + AT_THR)) {
;                     const float al = fast_exp2(mrun[cc] - mn); lrun[cc] *= al;
; #pragma unroll
;                     for (int r = 0; r < 16; ++r) { o[cc][0][r] *= al; o[cc][1][r] *= al; }
;                     mrun[cc] = mn;
;                 }
;                 mn = mrun[cc];
;                 if (MODE != 0) rmrel[cc] -= mn;
;                 const bool dead = (MODE != 0) && __all(rmrel[cc] < -136.f);
;                 if (dead) { pw[cc][0] = zero8; pw[cc][1] = zero8; }
;                 else {
;                     alive = true;
;                     if (MODE != 0) {
; #pragma unroll
;                         for (int r = 0; r < 16; ++r) s0[r] = fast_exp2(s0[r] - mn);
;                     } else {
;                         const float nm = -mn;
; #pragma unroll
;                         for (int r = 0; r < 16; ++r) s0[r] = fast_exp2(__builtin_fmaf(s0[r], c, nm));
;                     }
;                     u32x4 w;
;                     w.x = cvtpk(s0[0], s0[1]); w.y = cvtpk(s0[2], s0[3]); w.z = cvtpk(s0[4], s0[5]); w.w = cvtpk(s0[6], s0[7]); pw[cc][0] = __builtin_bit_cast(bf16x8, w);
.LBB0_428:
	v_fmamk_f32 v99, v80, 0x3e8293ee, v156
	v_fmamk_f32 v96, v81, 0x3e8293ee, v157
	v_max3_f32 v0, v99, s68, v96
	v_fmamk_f32 v97, v82, 0x3e8293ee, v158
	v_fmac_f32_e32 v159, 0x3e8293ee, v83
	v_max3_f32 v0, v0, v97, v159
	v_fmamk_f32 v98, v84, 0x3e8293ee, v152
	v_fmamk_f32 v82, v85, 0x3e8293ee, v153
	v_max3_f32 v0, v0, v98, v82
	v_fmamk_f32 v83, v86, 0x3e8293ee, v154
	v_fmac_f32_e32 v155, 0x3e8293ee, v87
	v_max3_f32 v0, v0, v83, v155
	v_fmamk_f32 v84, v88, 0x3e8293ee, v164
	v_fmamk_f32 v15, v89, 0x3e8293ee, v165
	v_max3_f32 v0, v0, v84, v15
	v_fmamk_f32 v80, v90, 0x3e8293ee, v166
	v_fmac_f32_e32 v167, 0x3e8293ee, v91
	v_max3_f32 v14, v0, v80, v167
	v_fmamk_f32 v81, v92, 0x3e8293ee, v172
	v_fmamk_f32 v0, v93, 0x3e8293ee, v173
	v_max3_f32 v85, v14, v81, v0
	v_fmamk_f32 v14, v94, 0x3e8293ee, v174
	v_fmac_f32_e32 v175, 0x3e8293ee, v95
	v_max3_f32 v85, v85, v14, v175
	v_mov_b32_e32 v86, v85
	s_nop 1
	v_permlane32_swap_b32_e32 v85, v86
	v_max_f32_e32 v85, v85, v86
	v_max_f32_e32 v197, v201, v85
	v_add_f32_e32 v86, 0x41000000, v201
	v_cmp_gt_f32_e32 vcc, v197, v86
	s_cbranch_vccz .LBB0_431
	v_sub_f32_e32 v86, v201, v197
	s_mov_b32 s61, 0
	v_exp_f32_e32 v86, v86
	s_nop 0
	v_mul_f32_e32 v187, v187, v86
	v_pk_mul_f32 v[62:63], v[62:63], v[86:87] op_sel_hi:[1,0]
	v_pk_mul_f32 v[60:61], v[60:61], v[86:87] op_sel_hi:[1,0]
	v_pk_mul_f32 v[58:59], v[58:59], v[86:87] op_sel_hi:[1,0]
	v_pk_mul_f32 v[56:57], v[56:57], v[86:87] op_sel_hi:[1,0]
	v_pk_mul_f32 v[54:55], v[54:55], v[86:87] op_sel_hi:[1,0]
	v_pk_mul_f32 v[52:53], v[52:53], v[86:87] op_sel_hi:[1,0]
	v_pk_mul_f32 v[50:51], v[50:51], v[86:87] op_sel_hi:[1,0]
	v_pk_mul_f32 v[48:49], v[48:49], v[86:87] op_sel_hi:[1,0]
	v_pk_mul_f32 v[46:47], v[46:47], v[86:87] op_sel_hi:[1,0]
	v_pk_mul_f32 v[44:45], v[44:45], v[86:87] op_sel_hi:[1,0]
	v_pk_mul_f32 v[42:43], v[42:43], v[86:87] op_sel_hi:[1,0]
	v_pk_mul_f32 v[40:41], v[40:41], v[86:87] op_sel_hi:[1,0]
	v_pk_mul_f32 v[38:39], v[38:39], v[86:87] op_sel_hi:[1,0]
	v_pk_mul_f32 v[36:37], v[36:37], v[86:87] op_sel_hi:[1,0]
	v_pk_mul_f32 v[34:35], v[34:35], v[86:87] op_sel_hi:[1,0]
	v_pk_mul_f32 v[32:33], v[32:33], v[86:87] op_sel_hi:[1,0]
	v_sub_f32_e32 v85, v85, v197
	v_cmp_gt_f32_e32 vcc, s30, v85
	s_cmp_eq_u64 vcc, exec
	s_cbranch_scc1 .LBB0_432
.LBB0_430:
	s_cmp_lg_u32 s61, 0
	s_cbranch_scc1 .Lr0_A4_fast
	v_sub_f32_e32 v85, v99, v197
	v_sub_f32_e32 v86, v96, v197
	v_sub_f32_e32 v87, v97, v197
	v_sub_f32_e32 v88, v159, v197
	v_sub_f32_e32 v89, v98, v197
	v_sub_f32_e32 v82, v82, v197
	v_sub_f32_e32 v83, v83, v197
	v_sub_f32_e32 v90, v155, v197
	v_exp_f32_e32 v85, v85
	v_exp_f32_e32 v86, v86
	v_exp_f32_e32 v87, v87
	v_exp_f32_e32 v88, v88
	v_exp_f32_e32 v89, v89
	v_exp_f32_e32 v82, v82
	v_exp_f32_e32 v83, v83
	v_exp_f32_e32 v90, v90
	v_sub_f32_e32 v84, v84, v197
	v_sub_f32_e32 v15, v15, v197
	v_sub_f32_e32 v80, v80, v197
	v_sub_f32_e32 v91, v167, v197
	v_sub_f32_e32 v81, v81, v197
	v_sub_f32_e32 v0, v0, v197
	v_sub_f32_e32 v14, v14, v197
	v_sub_f32_e32 v92, v175, v197
	v_exp_f32_e32 v84, v84
	v_exp_f32_e32 v15, v15
	v_exp_f32_e32 v80, v80
	v_exp_f32_e32 v91, v91
	v_exp_f32_e32 v81, v81
	v_exp_f32_e32 v0, v0
	v_exp_f32_e32 v14, v14
	v_exp_f32_e32 v92, v92
.Lr0_A4_join:
	v_cvt_pk_bf16_f32 v100, v85, v86
	v_cvt_pk_bf16_f32 v101, v87, v88
	v_cvt_pk_bf16_f32 v102, v89, v82
	v_cvt_pk_bf16_f32 v103, v83, v90
	v_cvt_pk_bf16_f32 v96, v84, v15
	v_cvt_pk_bf16_f32 v97, v80, v91
	v_cvt_pk_bf16_f32 v98, v81, v0
	v_cvt_pk_bf16_f32 v99, v14, v92
	v_mfma_f32_32x32x16_bf16 v[80:95], v[220:223], v[100:103], 0
	s_nop 0
	v_mfma_f32_32x32x16_bf16 v[80:95], v[220:223], v[96:99], v[80:95]
	s_nop 11
	v_add_f32_e32 v187, v187, v80
	s_branch .LBB0_433

; __device__ __forceinline__ float fast_exp2(float x) { return __builtin_amdgcn_exp2f(x); }
; template <int MODE, int NQ>
; __device__ __forceinline__ void attn_unit(LAS unsigned char* lds, const Params& P, int layer, int b, int h, int qb) {
;     ...
;                         for (int r = 0; r < 16; ++r) s0[r] = fast_exp2(s0[r] - mn);
.Lr0_A1_fast:
	v_exp_f32_e32 v108, v160
	v_exp_f32_e32 v109, v161
	v_exp_f32_e32 v98, v98
	v_exp_f32_e32 v99, v99
	v_exp_f32_e32 v14, v14
	v_exp_f32_e32 v15, v15
	v_exp_f32_e32 v96, v96
	v_exp_f32_e32 v97, v97
	v_exp_f32_e32 v104, v104
	v_exp_f32_e32 v105, v105
	v_exp_f32_e32 v100, v100
	v_exp_f32_e32 v101, v101
	v_exp_f32_e32 v102, v102
	v_exp_f32_e32 v103, v103
	v_exp_f32_e32 v106, v106
	v_exp_f32_e32 v107, v107
	s_branch .Lr0_A1_join
.Lr0_A2_fast:
	v_exp_f32_e32 v86, v99
	v_exp_f32_e32 v87, v96
	v_exp_f32_e32 v88, v97
	v_exp_f32_e32 v89, v159
	v_exp_f32_e32 v90, v98
	v_exp_f32_e32 v83, v83
	v_exp_f32_e32 v84, v84
	v_exp_f32_e32 v91, v155
	v_exp_f32_e32 v85, v85
	v_exp_f32_e32 v80, v80
	v_exp_f32_e32 v81, v81
	v_exp_f32_e32 v92, v167
	v_exp_f32_e32 v82, v82
	v_exp_f32_e32 v14, v14
	v_exp_f32_e32 v15, v15
	v_exp_f32_e32 v93, v175
	s_branch .Lr0_A2_join
.Lr0_A3_fast:
	v_exp_f32_e32 v0, v160
	v_exp_f32_e32 v108, v161
	v_exp_f32_e32 v98, v98
	v_exp_f32_e32 v99, v99
	v_exp_f32_e32 v14, v14
	v_exp_f32_e32 v15, v15
	v_exp_f32_e32 v96, v96
	v_exp_f32_e32 v97, v97
	v_exp_f32_e32 v104, v104
	v_exp_f32_e32 v105, v105
	v_exp_f32_e32 v100, v100
	v_exp_f32_e32 v101, v101
	v_exp_f32_e32 v102, v102
	v_exp_f32_e32 v103, v103
	v_exp_f32_e32 v106, v106
	v_exp_f32_e32 v107, v107
	s_branch .Lr0_A3_join
.Lr0_A4_fast:
	v_exp_f32_e32 v85, v99
	v_exp_f32_e32 v86, v96
	v_exp_f32_e32 v87, v97
	v_exp_f32_e32 v88, v159
	v_exp_f32_e32 v89, v98
	v_exp_f32_e32 v82, v82
	v_exp_f32_e32 v83, v83
	v_exp_f32_e32 v90, v155
	v_exp_f32_e32 v84, v84
	v_exp_f32_e32 v15, v15
	v_exp_f32_e32 v80, v80
	v_exp_f32_e32 v91, v167
	v_exp_f32_e32 v81, v81
	v_exp_f32_e32 v0, v0
	v_exp_f32_e32 v14, v14
	v_exp_f32_e32 v92, v175
	s_branch .Lr0_A4_join

; #define LAS __attribute__((address_space(3)))
; #define AT_GLOADK(kt) do { const size_t r_ = rowbase + (size_t)(kt) * 64; \
;         kreg = *(const u32x4*)(Kp + (r_ + lane) * kpitch + wave * 8); \
;         if (MODE == 0 && wave < 4) kreg2 = *(const u32x4*)(proj + (r_ + lane) * NPROJ + 1920 + wave * 8); } while (0)
; #define AT_GLOADV(kt) do { const size_t r_ = rowbase + (size_t)(kt) * 64; \
;         vreg = *(const u32x4*)(Vp + (r_ + 16 * (wave & 3) + (lane >> 2)) * vpitch + (wave >> 2) * 32 + (lane & 3) * 8); } while (0)
; #define AT_LSTOREV(buf) do { LAS unsigned char* d_ = lds + (buf) * AT_BUF; \
;         *(LAS u32x4*)(d_ + AT_V + wave * 1024 + lane * 16) = vreg; } while (0)
; template <int MODE, int NQ>
; __device__ __forceinline__ void attn_unit(LAS unsigned char* lds, const Params& P, int layer, int b, int h, int qb) {
;     ...
;     const int qpos0 = q0 + wave * (32 * NQ) + r32;
;     const int tb0_ = 4 * hi - qpos0 + 2047, ts_ = tb0_ & 3;
;     const LAS unsigned char* tlane = tabb + ts_ * AT_TABC + (tb0_ - ts_) * 4;
;     bf16x8 qf[NC][ND0];
; #pragma unroll
;     for (int jq = 0; jq < NQ; ++jq) {
;         const bf16_t* qrow = Qp + (rowbase + qpos0 + 32 * jq) * qpitch + hi * 8;
; #pragma unroll
;         for (int mp = 0; mp < NMAP; ++mp)
; #pragma unroll
;             for (int d0 = 0; d0 < ND0; ++d0) qf[jq * NMAP + mp][d0] = *(const bf16x8*)(qrow + mp * 32 + d0 * 16);
;     }
;     u32x4 kreg, kreg2 = (u32x4){0u, 0u, 0u, 0u}, vreg;
;     ...
;     float mrun[NC], lrun[NC]; f32x16 o[NC][2];
; #pragma unroll
;     for (int cc = 0; cc < NC; ++cc) { mrun[cc] = -1e20f; lrun[cc] = 0.f; o[cc][0] = f32x16{}; o[cc][1] = f32x16{}; }
;     constexpr int NK = NMAP * ND0;
;     const bf16x8 ones8 = (bf16x8){0x3F80, 0x3F80, 0x3F80, 0x3F80, 0x3F80, 0x3F80, 0x3F80, 0x3F80};
;     const bf16x8 zero8 = (bf16x8){0, 0, 0, 0, 0, 0, 0, 0};
;     bf16x8 kf[NK]; s16x4 vlo[4], vhi[4];
;     ...
;     const int vlane = ((lane >> 4) & 1) * 32 + (lane & 3) * 8 + (4 * hi + ((lane & 15) >> 2)) * 64;
;     const int NT = kt1 - kt0, ks = (MODE != 0) ? (q0 / 64 - kt0) : 0;
;     ...
;     AT_GLOADK(AT_TILE(0)); AT_GLOADV(AT_TILE(0)); AT_LSTOREK(0); AT_LSTOREV(0);
;     if (1 < NT) { AT_GLOADK(AT_TILE(1)); AT_GLOADV(AT_TILE(1)); AT_LSTOREK(1); AT_LSTOREV(1); }
;     __syncthreads();
;     AT_KLOAD(lds, 0);
;     if (wave >= 4) __builtin_amdgcn_s_setprio(1);
;     int bcur = 0;
.LBB0_501:
	v_lshlrev_b32_e32 v7, 2, v6
	v_sub_u32_e32 v4, v7, v4
	s_lshl_b32 s9, s9, 6
	v_add_u32_e32 v4, 0x7ff, v4
	v_lshlrev_b32_e32 v129, 3, v6
	v_lshlrev_b32_e32 v6, 1, v2
	v_lshrrev_b32_e32 v2, 2, v2
	v_and_b32_e32 v8, 3, v4
	v_and_or_b32 v2, v2, 3, v7
	s_add_u32 s14, s14, s22
	v_mul_u32_u24_e32 v8, 0x4040, v8
	v_lshlrev_b32_e32 v4, 2, v4
	v_lshlrev_b32_e32 v131, 6, v2
	v_mov_b32_e32 v2, s21
	s_addc_u32 s15, s15, s23
	v_and_b32_e32 v4, -16, v4
	v_or3_b32 v118, s0, v2, v5
	v_lshl_add_u64 v[120:121], s[14:15], 0, v[0:1]
	v_or_b32_e32 v122, s0, v3
	s_add_u32 s0, s10, s16
	v_lshl_add_u32 v0, s19, 10, v8
	v_readlane_b32 s10, v252, 25
	v_mov_b32_e32 v14, v1
	v_mov_b32_e32 v15, v1
	v_and_b32_e32 v130, 32, v6
	v_add3_u32 v133, v0, v4, s10
	v_mov_b32_e32 v0, v1
	v_mov_b32_e32 v2, v1
	v_mov_b32_e32 v3, v1
	v_mov_b32_e32 v4, v1
	v_mov_b32_e32 v5, v1
	v_mov_b32_e32 v6, v1
	v_mov_b32_e32 v7, v1
	v_mov_b32_e32 v8, v1
	v_mov_b32_e32 v9, v1
	v_mov_b32_e32 v10, v1
	v_mov_b32_e32 v11, v1
	v_mov_b32_e32 v12, v1
	v_mov_b32_e32 v13, v1
	v_mov_b64_e32 v[30:31], v[14:15]
	v_mov_b64_e32 v[46:47], v[14:15]
	s_mov_b32 s18, 2
	v_or3_b32 v119, s1, 0, 0
	v_mov_b32_e32 v123, s1
	s_addc_u32 s1, s11, s17
	s_mov_b32 s19, 0
	v_mov_b32_e32 v134, 0
	v_mov_b32_e32 v132, 0
	v_mov_b64_e32 v[28:29], v[12:13]
	v_mov_b64_e32 v[26:27], v[10:11]
	v_mov_b64_e32 v[24:25], v[8:9]
	v_mov_b64_e32 v[22:23], v[6:7]
	v_mov_b64_e32 v[20:21], v[4:5]
	v_mov_b64_e32 v[18:19], v[2:3]
	v_mov_b64_e32 v[16:17], v[0:1]
	v_mov_b64_e32 v[44:45], v[12:13]
	v_mov_b64_e32 v[42:43], v[10:11]
	v_mov_b64_e32 v[40:41], v[8:9]
	v_mov_b64_e32 v[38:39], v[6:7]
	v_mov_b64_e32 v[36:37], v[4:5]
	v_mov_b64_e32 v[34:35], v[2:3]
	v_mov_b64_e32 v[32:33], v[0:1]
	v_mov_b32_e32 v220, s60
	v_mov_b32_e32 v221, s60
	v_mov_b32_e32 v222, s60
	v_mov_b32_e32 v223, s60
	s_mov_b32 s61, 1
	s_branch .LBB0_503

; #define LAS __attribute__((address_space(3)))
; __device__ __forceinline__ float fast_exp2(float x) { return __builtin_amdgcn_exp2f(x); }
; template <int MODE, int NQ>
; __device__ __forceinline__ void attn_unit(LAS unsigned char* lds, const Params& P, int layer, int b, int h, int qb) {
;     ...
;         for (int hf = 0; hf < 2; ++hf) {
;             if (it + 2 < NT) { if (hf == 0) AT_GLOADK(AT_TILE(it + 2)); else AT_GLOADV(AT_TILE(it + 2)); }
;             f32x16 sc[NC];
; #pragma unroll
;             for (int cc = 0; cc < NC; ++cc) {
;                 sc[cc] = f32x16{};
; #pragma unroll
;                 for (int d0 = 0; d0 < ND0; ++d0) sc[cc] = __builtin_amdgcn_mfma_f32_32x32x16_bf16(kf[(cc % NMAP) * ND0 + d0], qf[cc][d0], sc[cc], 0, 0, 0);
;             }
;             __builtin_amdgcn_sched_barrier(0);
;             AT_VLOAD(cur, hf);
;             if (hf == 0) AT_KLOAD(cur, 1); else if (it + 1 < NT) AT_KLOAD(nxt, 0);
;             __builtin_amdgcn_sched_barrier(0);
;             bf16x8 pw[NC][2]; float rmrel[NC]; bool alive = false;
; #pragma unroll
;             for (int cc = 0; cc < NC; ++cc) {
;                 f32x16& s0 = sc[cc];
;                 float mn;
;                 if (MODE != 0) {
;                     const LAS f32x4* tp4 = (const LAS f32x4*)(tlane + (kt * 64 + hf * 32) * 4);
;                     float rm = -3e38f;
; #pragma unroll
;                     for (int g = 0; g < 4; ++g) { const f32x4 t4 = tp4[2 * g];
; #pragma unroll
;                         for (int i = 0; i < 4; ++i) { s0[4 * g + i] = s0[4 * g + i] * c + t4[i]; rm = fmaxf(rm, s0[4 * g + i]); } }
;                     rm = xmax(rm);
;                     mn = fmaxf(mrun[cc], rm);
;                     rmrel[cc] = rm;
;                 } else {
;                     float rm = -3e38f;
; #pragma unroll
;                     for (int r = 0; r < 16; ++r) rm = fmaxf(rm, s0[r]);
;                     rm = xmax(rm);
;                     mn = fmaxf(mrun[cc], rm * c);
;                 }
;                 if (__any(mn > mrun[cc] + AT_THR)) {
;                     const float al = fast_exp2(mrun[cc] - mn); lrun[cc] *= al;
; #pragma unroll
;                     for (int r = 0; r < 16; ++r) { o[cc][0][r] *= al; o[cc][1][r] *= al; }
;                     mrun[cc] = mn;
;                 }
.LBB0_505:
	s_add_i32 s16, s16, -2
	s_cmp_ge_i32 s16, s6
	s_mul_i32 s17, s19, 0x5000
	s_cselect_b32 s16, s6, 0
	s_add_i32 s17, s17, 0
	v_add3_u32 v0, s17, v130, v131
	s_lshl_b32 s20, s16, 8
	s_waitcnt lgkmcnt(3)
	v_mfma_f32_32x32x16_bf16 v[48:63], v[96:99], v[64:67], 0
	v_add_u32_e32 v15, v0, v124
	ds_read_b64_tr_b16 v[2:3], v15 offset:12288
	ds_read_b64_tr_b16 v[4:5], v15 offset:12800
	ds_read_b64_tr_b16 v[6:7], v15 offset:13312
	ds_read_b64_tr_b16 v[8:9], v15 offset:13824
	ds_read_b64_tr_b16 v[10:11], v15 offset:16384
	ds_read_b64_tr_b16 v[12:13], v15 offset:16896
	ds_read_b64_tr_b16 v[104:105], v15 offset:17408
	ds_read_b64_tr_b16 v[106:107], v15 offset:17920
	v_add3_u32 v0, s17, v126, v127
	s_waitcnt lgkmcnt(10)
	v_mfma_f32_32x32x16_bf16 v[48:63], v[100:103], v[68:71], v[48:63]
	ds_read_b128 v[96:99], v0 offset:512
	ds_read_b128 v[100:103], v0 offset:2560
	s_waitcnt lgkmcnt(11)
	v_mfma_f32_32x32x16_bf16 v[48:63], v[92:95], v[72:75], v[48:63]
	s_waitcnt lgkmcnt(10)
	v_mfma_f32_32x32x16_bf16 v[48:63], v[88:91], v[76:79], v[48:63]
	ds_read_b128 v[92:95], v0 offset:4608
	ds_read_b128 v[88:91], v0 offset:6656
	v_subrev_u32_e32 v0, s20, v133
	ds_read_b128 v[112:115], v0
	ds_read_b128 v[108:111], v0 offset:32
	s_waitcnt lgkmcnt(1)
	s_nop 5
	v_fmamk_f32 v135, v48, 0x3e38aa3b, v112
	v_fmamk_f32 v14, v49, 0x3e38aa3b, v113
	v_fmamk_f32 v112, v50, 0x3e38aa3b, v114
	v_fmac_f32_e32 v115, 0x3e38aa3b, v51
	v_max3_f32 v48, v135, s68, v14
	v_max3_f32 v48, v48, v112, v115
	s_waitcnt lgkmcnt(0)
	v_fmamk_f32 v113, v52, 0x3e38aa3b, v108
	v_fmamk_f32 v108, v53, 0x3e38aa3b, v109
	v_max3_f32 v52, v48, v113, v108
	ds_read_b128 v[48:51], v0 offset:64
	v_fmamk_f32 v109, v54, 0x3e38aa3b, v110
	v_fmac_f32_e32 v111, 0x3e38aa3b, v55
	v_max3_f32 v114, v52, v109, v111
	ds_read_b128 v[52:55], v0 offset:96
	s_waitcnt lgkmcnt(1)
	v_fmamk_f32 v110, v56, 0x3e38aa3b, v48
	v_fmamk_f32 v56, v57, 0x3e38aa3b, v49
	v_max3_f32 v0, v114, v110, v56
	v_fmamk_f32 v57, v58, 0x3e38aa3b, v50
	v_fmac_f32_e32 v51, 0x3e38aa3b, v59
	v_max3_f32 v0, v0, v57, v51
	s_waitcnt lgkmcnt(0)
	v_fmamk_f32 v50, v60, 0x3e38aa3b, v52
	v_fmamk_f32 v48, v61, 0x3e38aa3b, v53
	v_max3_f32 v0, v0, v50, v48
	v_fmamk_f32 v49, v62, 0x3e38aa3b, v54
	v_fmac_f32_e32 v55, 0x3e38aa3b, v63
	v_max3_f32 v0, v0, v49, v55
	v_mov_b32_e32 v52, v0
	s_nop 1
	v_permlane32_swap_b32_e32 v0, v52
	v_max_f32_e32 v52, v0, v52
	v_max_f32_e32 v0, v134, v52
	v_add_f32_e32 v53, 0x41000000, v134
	v_cmp_gt_f32_e32 vcc, v0, v53
	s_cbranch_vccz .LBB0_507
	v_sub_f32_e32 v53, v134, v0
	s_mov_b32 s61, 0
	v_exp_f32_e32 v54, v53
	s_nop 0
	v_pk_mul_f32 v[46:47], v[46:47], v[54:55] op_sel_hi:[1,0]
	v_pk_mul_f32 v[44:45], v[44:45], v[54:55] op_sel_hi:[1,0]
	v_pk_mul_f32 v[42:43], v[42:43], v[54:55] op_sel_hi:[1,0]
	v_pk_mul_f32 v[40:41], v[40:41], v[54:55] op_sel_hi:[1,0]
	v_pk_mul_f32 v[38:39], v[38:39], v[54:55] op_sel_hi:[1,0]
	v_pk_mul_f32 v[36:37], v[36:37], v[54:55] op_sel_hi:[1,0]
	v_pk_mul_f32 v[34:35], v[34:35], v[54:55] op_sel_hi:[1,0]
	v_pk_mul_f32 v[32:33], v[32:33], v[54:55] op_sel_hi:[1,0]
	v_pk_mul_f32 v[30:31], v[30:31], v[54:55] op_sel_hi:[1,0]
	v_pk_mul_f32 v[28:29], v[28:29], v[54:55] op_sel_hi:[1,0]
	v_pk_mul_f32 v[26:27], v[26:27], v[54:55] op_sel_hi:[1,0]
	v_pk_mul_f32 v[24:25], v[24:25], v[54:55] op_sel_hi:[1,0]
	v_pk_mul_f32 v[22:23], v[22:23], v[54:55] op_sel_hi:[1,0]
	v_pk_mul_f32 v[20:21], v[20:21], v[54:55] op_sel_hi:[1,0]
	v_pk_mul_f32 v[18:19], v[18:19], v[54:55] op_sel_hi:[1,0]
	v_pk_mul_f32 v[16:17], v[16:17], v[54:55] op_sel_hi:[1,0]
	v_mul_f32_e32 v132, v132, v54
	s_branch .LBB0_508

; __device__ __forceinline__ unsigned cvtpk(float lo, float hi) { f32x2 v = {lo, hi}; bf16x2_t b = __builtin_convertvector(v, bf16x2_t); return __builtin_bit_cast(unsigned, b); }
; __device__ __forceinline__ float fast_exp2(float x) { return __builtin_amdgcn_exp2f(x); }
; template <int MODE, int NQ>
; __device__ __forceinline__ void attn_unit(LAS unsigned char* lds, const Params& P, int layer, int b, int h, int qb) {
;     ...
;                 mn = mrun[cc];
;                 if (MODE != 0) rmrel[cc] -= mn;
;                 const bool dead = (MODE != 0) && __all(rmrel[cc] < -136.f);
;                 if (dead) { pw[cc][0] = zero8; pw[cc][1] = zero8; }
;                 else {
;                     alive = true;
;                     if (MODE != 0) {
; #pragma unroll
;                         for (int r = 0; r < 16; ++r) s0[r] = fast_exp2(s0[r] - mn);
;                     } else {
;                         const float nm = -mn;
; #pragma unroll
;                         for (int r = 0; r < 16; ++r) s0[r] = fast_exp2(__builtin_fmaf(s0[r], c, nm));
;                     }
;                     u32x4 w;
;                     w.x = cvtpk(s0[0], s0[1]); w.y = cvtpk(s0[2], s0[3]); w.z = cvtpk(s0[4], s0[5]); w.w = cvtpk(s0[6], s0[7]); pw[cc][0] = __builtin_bit_cast(bf16x8, w);
;                     w.x = cvtpk(s0[8], s0[9]); w.y = cvtpk(s0[10], s0[11]); w.z = cvtpk(s0[12], s0[13]); w.w = cvtpk(s0[14], s0[15]); pw[cc][1] = __builtin_bit_cast(bf16x8, w);
;                     f32x16 t = __builtin_amdgcn_mfma_f32_32x32x16_bf16(ones8, pw[cc][0], f32x16{}, 0, 0, 0);
;                     t = __builtin_amdgcn_mfma_f32_32x32x16_bf16(ones8, pw[cc][1], t, 0, 0, 0);
;                     lrun[cc] += t[0];
.LBB0_508:
	v_sub_f32_e32 v52, v52, v0
	v_cmp_gt_f32_e32 vcc, s30, v52
	s_cmp_lg_u64 vcc, exec
	s_cselect_b64 s[16:17], -1, 0
	s_cmp_eq_u64 vcc, exec
	s_cbranch_scc1 .LBB0_510
	s_cmp_lg_u32 s61, 0
	s_cbranch_scc1 .Lr0_B1_fast
	v_sub_f32_e32 v52, v135, v0
	v_sub_f32_e32 v14, v14, v0
	v_sub_f32_e32 v53, v112, v0
	v_sub_f32_e32 v54, v115, v0
	v_sub_f32_e32 v58, v113, v0
	v_sub_f32_e32 v59, v108, v0
	v_sub_f32_e32 v60, v109, v0
	v_sub_f32_e32 v61, v111, v0
	v_exp_f32_e32 v52, v52
	v_exp_f32_e32 v14, v14
	v_exp_f32_e32 v53, v53
	v_exp_f32_e32 v54, v54
	v_exp_f32_e32 v58, v58
	v_exp_f32_e32 v59, v59
	v_exp_f32_e32 v60, v60
	v_exp_f32_e32 v61, v61
	v_sub_f32_e32 v62, v110, v0
	v_sub_f32_e32 v56, v56, v0
	v_sub_f32_e32 v57, v57, v0
	v_sub_f32_e32 v51, v51, v0
	v_sub_f32_e32 v50, v50, v0
	v_sub_f32_e32 v48, v48, v0
	v_sub_f32_e32 v49, v49, v0
	v_sub_f32_e32 v55, v55, v0
	v_exp_f32_e32 v62, v62
	v_exp_f32_e32 v56, v56
	v_exp_f32_e32 v57, v57
	v_exp_f32_e32 v51, v51
	v_exp_f32_e32 v50, v50
	v_exp_f32_e32 v48, v48
	v_exp_f32_e32 v49, v49
	v_exp_f32_e32 v55, v55
.Lr0_B1_join:
	v_cvt_pk_bf16_f32 v112, v52, v14
	v_cvt_pk_bf16_f32 v113, v53, v54
	v_cvt_pk_bf16_f32 v114, v58, v59
	v_cvt_pk_bf16_f32 v115, v60, v61
	v_cvt_pk_bf16_f32 v108, v62, v56
	v_cvt_pk_bf16_f32 v109, v57, v51
	v_cvt_pk_bf16_f32 v110, v50, v48
	v_cvt_pk_bf16_f32 v111, v49, v55
	v_mfma_f32_32x32x16_bf16 v[48:63], v[220:223], v[112:115], 0
	s_nop 0
	v_mfma_f32_32x32x16_bf16 v[48:63], v[220:223], v[108:111], v[48:63]
	s_nop 11
	v_add_f32_e32 v132, v132, v48
	s_andn2_b64 vcc, exec, s[16:17]
	s_cbranch_vccz .LBB0_511
	s_branch .LBB0_512

; #define LAS __attribute__((address_space(3)))
; __device__ __forceinline__ float fast_exp2(float x) { return __builtin_amdgcn_exp2f(x); }
; __device__ __forceinline__ float xmax(float a) { auto rr = __builtin_amdgcn_permlane32_swap(__float_as_uint(a), __float_as_uint(a), false, false); return fmaxf(__uint_as_float(rr[0]), __uint_as_float(rr[1])); }
; template <int MODE, int NQ>
; __device__ __forceinline__ void attn_unit(LAS unsigned char* lds, const Params& P, int layer, int b, int h, int qb) {
;     ...
;             for (int cc = 0; cc < NC; ++cc) {
;                 f32x16& s0 = sc[cc];
;                 float mn;
;                 if (MODE != 0) {
;                     const LAS f32x4* tp4 = (const LAS f32x4*)(tlane + (kt * 64 + hf * 32) * 4);
;                     float rm = -3e38f;
; #pragma unroll
;                     for (int g = 0; g < 4; ++g) { const f32x4 t4 = tp4[2 * g];
; #pragma unroll
;                         for (int i = 0; i < 4; ++i) { s0[4 * g + i] = s0[4 * g + i] * c + t4[i]; rm = fmaxf(rm, s0[4 * g + i]); } }
;                     rm = xmax(rm);
;                     mn = fmaxf(mrun[cc], rm);
;                     rmrel[cc] = rm;
;                 } else {
;                     float rm = -3e38f;
; #pragma unroll
;                     for (int r = 0; r < 16; ++r) rm = fmaxf(rm, s0[r]);
;                     rm = xmax(rm);
;                     mn = fmaxf(mrun[cc], rm * c);
;                 }
;                 if (__any(mn > mrun[cc] + AT_THR)) {
;                     const float al = fast_exp2(mrun[cc] - mn); lrun[cc] *= al;
; #pragma unroll
;                     for (int r = 0; r < 16; ++r) { o[cc][0][r] *= al; o[cc][1][r] *= al; }
;                     mrun[cc] = mn;
;                 }
.LBB0_516:
	s_sub_i32 s10, 0, s20
	v_add_u32_e32 v134, s10, v133
	ds_read_b128 v[112:115], v134 offset:128
	ds_read_b128 v[108:111], v134 offset:160
	s_waitcnt lgkmcnt(1)
	s_nop 5
	v_fmamk_f32 v135, v48, 0x3e38aa3b, v112
	v_fmamk_f32 v15, v49, 0x3e38aa3b, v113
	v_fmamk_f32 v112, v50, 0x3e38aa3b, v114
	v_fmac_f32_e32 v115, 0x3e38aa3b, v51
	v_max3_f32 v48, v135, s68, v15
	v_max3_f32 v48, v48, v112, v115
	s_waitcnt lgkmcnt(0)
	v_fmamk_f32 v113, v52, 0x3e38aa3b, v108
	v_fmamk_f32 v108, v53, 0x3e38aa3b, v109
	v_max3_f32 v52, v48, v113, v108
	ds_read_b128 v[48:51], v134 offset:192
	v_fmamk_f32 v109, v54, 0x3e38aa3b, v110
	v_fmac_f32_e32 v111, 0x3e38aa3b, v55
	v_max3_f32 v114, v52, v109, v111
	ds_read_b128 v[52:55], v134 offset:224
	s_waitcnt lgkmcnt(1)
	v_fmamk_f32 v110, v56, 0x3e38aa3b, v48
	v_fmamk_f32 v56, v57, 0x3e38aa3b, v49
	v_max3_f32 v48, v114, v110, v56
	v_fmamk_f32 v57, v58, 0x3e38aa3b, v50
	v_fmac_f32_e32 v51, 0x3e38aa3b, v59
	v_max3_f32 v49, v48, v57, v51
	s_waitcnt lgkmcnt(0)
	v_fmamk_f32 v50, v60, 0x3e38aa3b, v52
	v_fmamk_f32 v48, v61, 0x3e38aa3b, v53
	v_max3_f32 v52, v49, v50, v48
	v_fmamk_f32 v49, v62, 0x3e38aa3b, v54
	v_fmac_f32_e32 v55, 0x3e38aa3b, v63
	v_max3_f32 v52, v52, v49, v55
	v_mov_b32_e32 v53, v52
	s_nop 1
	v_permlane32_swap_b32_e32 v52, v53
	v_max_f32_e32 v52, v52, v53
	v_max_f32_e32 v134, v0, v52
	v_add_f32_e32 v53, 0x41000000, v0
	v_cmp_gt_f32_e32 vcc, v134, v53
	s_cbranch_vccz .LBB0_518
	v_sub_f32_e32 v0, v0, v134
	s_mov_b32 s61, 0
	v_exp_f32_e32 v0, v0
	s_nop 0
	v_pk_mul_f32 v[46:47], v[46:47], v[0:1] op_sel_hi:[1,0]
	v_pk_mul_f32 v[44:45], v[44:45], v[0:1] op_sel_hi:[1,0]
	v_pk_mul_f32 v[42:43], v[42:43], v[0:1] op_sel_hi:[1,0]
	v_pk_mul_f32 v[40:41], v[40:41], v[0:1] op_sel_hi:[1,0]
	v_pk_mul_f32 v[38:39], v[38:39], v[0:1] op_sel_hi:[1,0]
	v_pk_mul_f32 v[36:37], v[36:37], v[0:1] op_sel_hi:[1,0]
	v_pk_mul_f32 v[34:35], v[34:35], v[0:1] op_sel_hi:[1,0]
	v_pk_mul_f32 v[32:33], v[32:33], v[0:1] op_sel_hi:[1,0]
	v_pk_mul_f32 v[30:31], v[30:31], v[0:1] op_sel_hi:[1,0]
	v_pk_mul_f32 v[28:29], v[28:29], v[0:1] op_sel_hi:[1,0]
	v_pk_mul_f32 v[26:27], v[26:27], v[0:1] op_sel_hi:[1,0]
	v_pk_mul_f32 v[24:25], v[24:25], v[0:1] op_sel_hi:[1,0]
	v_pk_mul_f32 v[22:23], v[22:23], v[0:1] op_sel_hi:[1,0]
	v_pk_mul_f32 v[20:21], v[20:21], v[0:1] op_sel_hi:[1,0]
	v_pk_mul_f32 v[18:19], v[18:19], v[0:1] op_sel_hi:[1,0]
	v_pk_mul_f32 v[16:17], v[16:17], v[0:1] op_sel_hi:[1,0]
	v_mul_f32_e32 v132, v132, v0
	s_branch .LBB0_519

; __device__ __forceinline__ unsigned cvtpk(float lo, float hi) { f32x2 v = {lo, hi}; bf16x2_t b = __builtin_convertvector(v, bf16x2_t); return __builtin_bit_cast(unsigned, b); }
; __device__ __forceinline__ float fast_exp2(float x) { return __builtin_amdgcn_exp2f(x); }
; template <int MODE, int NQ>
; __device__ __forceinline__ void attn_unit(LAS unsigned char* lds, const Params& P, int layer, int b, int h, int qb) {
;     ...
;                 mn = mrun[cc];
;                 if (MODE != 0) rmrel[cc] -= mn;
;                 const bool dead = (MODE != 0) && __all(rmrel[cc] < -136.f);
;                 if (dead) { pw[cc][0] = zero8; pw[cc][1] = zero8; }
;                 else {
;                     alive = true;
;                     if (MODE != 0) {
; #pragma unroll
;                         for (int r = 0; r < 16; ++r) s0[r] = fast_exp2(s0[r] - mn);
;                     } else {
;                         const float nm = -mn;
; #pragma unroll
;                         for (int r = 0; r < 16; ++r) s0[r] = fast_exp2(__builtin_fmaf(s0[r], c, nm));
;                     }
;                     u32x4 w;
;                     w.x = cvtpk(s0[0], s0[1]); w.y = cvtpk(s0[2], s0[3]); w.z = cvtpk(s0[4], s0[5]); w.w = cvtpk(s0[6], s0[7]); pw[cc][0] = __builtin_bit_cast(bf16x8, w);
;                     w.x = cvtpk(s0[8], s0[9]); w.y = cvtpk(s0[10], s0[11]); w.z = cvtpk(s0[12], s0[13]); w.w = cvtpk(s0[14], s0[15]); pw[cc][1] = __builtin_bit_cast(bf16x8, w);
;                     f32x16 t = __builtin_amdgcn_mfma_f32_32x32x16_bf16(ones8, pw[cc][0], f32x16{}, 0, 0, 0);
;                     t = __builtin_amdgcn_mfma_f32_32x32x16_bf16(ones8, pw[cc][1], t, 0, 0, 0);
;                     lrun[cc] += t[0];
.LBB0_519:
	v_sub_f32_e32 v0, v52, v134
	v_cmp_gt_f32_e32 vcc, s30, v0
	s_cmp_lg_u64 vcc, exec
	s_cselect_b64 s[10:11], -1, 0
	s_cmp_eq_u64 vcc, exec
	s_cbranch_scc1 .LBB0_521
	s_cmp_lg_u32 s61, 0
	s_cbranch_scc1 .Lr0_B2_fast
	v_sub_f32_e32 v0, v135, v134
	v_sub_f32_e32 v15, v15, v134
	v_sub_f32_e32 v52, v112, v134
	v_sub_f32_e32 v53, v115, v134
	v_sub_f32_e32 v54, v113, v134
	v_sub_f32_e32 v58, v108, v134
	v_sub_f32_e32 v59, v109, v134
	v_sub_f32_e32 v60, v111, v134
	v_exp_f32_e32 v0, v0
	v_exp_f32_e32 v15, v15
	v_exp_f32_e32 v52, v52
	v_exp_f32_e32 v53, v53
	v_exp_f32_e32 v54, v54
	v_exp_f32_e32 v58, v58
	v_exp_f32_e32 v59, v59
	v_exp_f32_e32 v60, v60
	v_sub_f32_e32 v61, v110, v134
	v_sub_f32_e32 v56, v56, v134
	v_sub_f32_e32 v57, v57, v134
	v_sub_f32_e32 v51, v51, v134
	v_sub_f32_e32 v50, v50, v134
	v_sub_f32_e32 v48, v48, v134
	v_sub_f32_e32 v49, v49, v134
	v_sub_f32_e32 v55, v55, v134
	v_exp_f32_e32 v61, v61
	v_exp_f32_e32 v56, v56
	v_exp_f32_e32 v57, v57
	v_exp_f32_e32 v51, v51
	v_exp_f32_e32 v50, v50
	v_exp_f32_e32 v48, v48
	v_exp_f32_e32 v49, v49
	v_exp_f32_e32 v55, v55
.Lr0_B2_join:
	v_cvt_pk_bf16_f32 v112, v0, v15
	v_cvt_pk_bf16_f32 v113, v52, v53
	v_cvt_pk_bf16_f32 v114, v54, v58
	v_cvt_pk_bf16_f32 v115, v59, v60
	v_cvt_pk_bf16_f32 v108, v61, v56
	v_cvt_pk_bf16_f32 v109, v57, v51
	v_cvt_pk_bf16_f32 v110, v50, v48
	v_cvt_pk_bf16_f32 v111, v49, v55
	v_mfma_f32_32x32x16_bf16 v[48:63], v[220:223], v[112:115], 0
	s_nop 0
	v_mfma_f32_32x32x16_bf16 v[48:63], v[220:223], v[108:111], v[48:63]
	s_nop 11
	v_add_f32_e32 v132, v132, v48
	s_andn2_b64 vcc, exec, s[10:11]
	s_cbranch_vccz .LBB0_522
	s_branch .LBB0_523

; __device__ __forceinline__ float fast_exp2(float x) { return __builtin_amdgcn_exp2f(x); }
; template <int MODE, int NQ>
; __device__ __forceinline__ void attn_unit(LAS unsigned char* lds, const Params& P, int layer, int b, int h, int qb) {
;     ...
;                         for (int r = 0; r < 16; ++r) s0[r] = fast_exp2(s0[r] - mn);
.Lr0_B1_fast:
	v_exp_f32_e32 v52, v135
	v_exp_f32_e32 v14, v14
	v_exp_f32_e32 v53, v112
	v_exp_f32_e32 v54, v115
	v_exp_f32_e32 v58, v113
	v_exp_f32_e32 v59, v108
	v_exp_f32_e32 v60, v109
	v_exp_f32_e32 v61, v111
	v_exp_f32_e32 v62, v110
	v_exp_f32_e32 v56, v56
	v_exp_f32_e32 v57, v57
	v_exp_f32_e32 v51, v51
	v_exp_f32_e32 v50, v50
	v_exp_f32_e32 v48, v48
	v_exp_f32_e32 v49, v49
	v_exp_f32_e32 v55, v55
	s_branch .Lr0_B1_join
.Lr0_B2_fast:
	v_exp_f32_e32 v0, v135
	v_exp_f32_e32 v15, v15
	v_exp_f32_e32 v52, v112
	v_exp_f32_e32 v53, v115
	v_exp_f32_e32 v54, v113
	v_exp_f32_e32 v58, v108
	v_exp_f32_e32 v59, v109
	v_exp_f32_e32 v60, v111
	v_exp_f32_e32 v61, v110
	v_exp_f32_e32 v56, v56
	v_exp_f32_e32 v57, v57
	v_exp_f32_e32 v51, v51
	v_exp_f32_e32 v50, v50
	v_exp_f32_e32 v48, v48
	v_exp_f32_e32 v49, v49
	v_exp_f32_e32 v55, v55
	s_branch .Lr0_B2_join
